# GEMM phase prologues: K-tile 1's six LDS-DMA loads issued together with K-tile 0's eight, one counted vmcnt(8) wait (prologue de-serialisation), on top of v64
# baseline (speedup 1.0000x reference)
; #define PG8_STAGE(bufoff, gbase, voff) do { _Pragma("unroll") for (int _i = 0; _i < 2; ++_i) \
;         __builtin_amdgcn_global_load_lds((const unsigned*)((const char*)(gbase) + (voff)[_i]), (PG8_LAS unsigned*)(lds + (bufoff) + ldsw + _i * 8192), 16, 0, 0); } while (0)
; #define PG8_WAIT_V(n) asm volatile("s_waitcnt vmcnt(" #n ")" ::: "memory")
; #define PG8_BAR __builtin_amdgcn_s_barrier()
; template <class Epi, class Sched, bool ALIGN_EPI = false, bool SP2 = false>
; __device__ __forceinline__ void gemm_phase(PG8_LAS unsigned char* lds, const Gemm g, const Sched& S, const Epi& E) {
;     ...
;     if constexpr (SP2) {
;         PG8_STAGE(PG8_SB(0, 0), cB, voffB); PG8_STAGE(PG8_SB(0, 1), cB + hstep, voffB); PG8_STAGE(PG8_SA(0, 0), cA, voffA); PG8_STAGE(PG8_SA(0, 1), cA + hstep, voffA);
;         if (wr == 1) PG8_BAR;
;         PG8_WAIT_V(2); PG8_BAR;
;         PG8_STAGE(PG8_SB(1, 0), cB + kstep, voffB); PG8_STAGE(PG8_SA(1, 0), cA + kstep, voffA); PG8_STAGE(PG8_SB(1, 1), cB + hstep + kstep, voffB);
;         PG8_WAIT_V(6); PG8_BAR;
.LBB0_81:
	s_and_b32 s0, s0, 3
	s_lshl_b32 s5, s1, 13
	s_lshl_b32 s57, s0, 12
	s_add_u32 s8, s30, 0x100000
	s_addc_u32 s9, s31, 0
	s_add_u32 s16, s30, 0x6200000
	s_addc_u32 s17, s31, 0
	s_add_u32 s20, s30, 0x9200000
	s_addc_u32 s21, s31, 0
	s_add_u32 s22, s30, 0x9e00000
	s_mov_b64 s[26:27], 0x80
	s_addc_u32 s23, s31, 0
	s_add_i32 m0, s25, 0x18000
	v_lshl_add_u64 v[6:7], v[6:7], 0, s[26:27]
	global_load_lds_dwordx4 v[6:7], off
	v_lshl_add_u64 v[4:5], v[4:5], 0, s[26:27]
	s_add_i32 m0, s25, 0x1a000
	s_add_i32 s69, s25, 0x8000
	s_add_i32 s70, s25, 0xa000
	global_load_lds_dwordx4 v[4:5], off
	v_lshl_add_u64 v[0:1], v[0:1], 0, s[26:27]
	s_mov_b32 m0, s69
	s_add_u32 s72, s84, 0x80080
	global_load_lds_dwordx4 v[0:1], off
	v_lshl_add_u64 v[0:1], v[2:3], 0, s[26:27]
	s_mov_b32 m0, s70
	s_addc_u32 s73, s85, 0
	global_load_lds_dwordx4 v[0:1], off
	s_add_i32 m0, s25, 0x1c000
	v_lshl_add_u64 v[0:1], s[72:73], 0, v[138:139]
	global_load_lds_dwordx4 v[0:1], off
	v_lshl_add_u64 v[0:1], s[72:73], 0, v[142:143]
	s_add_i32 m0, s25, 0x1e000
	s_cmpk_lt_u32 s56, 0x100
	global_load_lds_dwordx4 v[0:1], off
	s_waitcnt vmcnt(8)
	s_barrier
	v_lshrrev_b32_e32 v1, 1, v8
	v_and_b32_e32 v1, 24, v1
	v_and_b32_e32 v0, 15, v8
	v_lshlrev_b32_e32 v2, 1, v1
	v_lshl_or_b32 v160, s1, 6, v0
	v_lshl_or_b32 v0, v0, 6, v2
	v_lshlrev_b32_e32 v2, 2, v8
	v_and_b32_e32 v2, 32, v2
	v_bitop3_b32 v3, v0, s5, v2 bitop3:0xde
	v_bitop3_b32 v161, v0, s57, v2 bitop3:0xde
	v_lshlrev_b32_e32 v0, 15, v9
	v_and_b32_e32 v0, 0xffff0000, v0
	v_lshl_or_b32 v146, s0, 5, v1
	v_lshl_add_u32 v0, v10, 12, v0
	v_and_b32_e32 v1, 1, v9
	v_lshl_or_b32 v0, v1, 6, v0
	v_lshl_add_u32 v150, v11, 1, v0
	v_lshlrev_b32_e32 v0, 15, v12
	v_and_b32_e32 v0, 0xffff0000, v0
	s_waitcnt vmcnt(6)
	s_cselect_b64 s[56:57], -1, 0
	s_cmp_gt_u32 s0, 1
	v_lshl_add_u32 v0, v13, 12, v0
	v_and_b32_e32 v1, 1, v12
	s_cselect_b64 s[76:77], -1, 0
	v_readlane_b32 s0, v254, 11
	v_lshlrev_b32_e32 v144, 2, v146
	v_lshl_or_b32 v0, v1, 6, v0
	s_add_i32 s74, 0, 0x10000
	s_add_i32 s75, 0, 0x14000
	s_ashr_i32 s71, s0, 31
	s_mov_b32 s72, s0
	s_ashr_i32 s73, s2, 31
	v_lshl_add_u64 v[148:149], s[60:61], 0, v[144:145]
	v_mov_b32_e32 v151, v145
	v_lshl_add_u32 v152, v14, 1, v0
	v_mov_b32_e32 v153, v145
	v_mov_b64_e32 v[154:155], 0x440
	v_mov_b64_e32 v[156:157], 0x43f
	v_add_u32_e32 v162, s74, v161
	v_add_u32_e32 v163, s75, v161
	v_add_u32_e32 v164, 0, v3
	s_barrier
	v_readlane_b32 s1, v254, 12
	s_branch .LBB0_84

; #define PG8_STAGE(bufoff, gbase, voff) do { _Pragma("unroll") for (int _i = 0; _i < 2; ++_i) \
;         __builtin_amdgcn_global_load_lds((const unsigned*)((const char*)(gbase) + (voff)[_i]), (PG8_LAS unsigned*)(lds + (bufoff) + ldsw + _i * 8192), 16, 0, 0); } while (0)
; #define PG8_WAIT_V(n) asm volatile("s_waitcnt vmcnt(" #n ")" ::: "memory")
; #define PG8_BAR __builtin_amdgcn_s_barrier()
; template <class Epi, class Sched, bool ALIGN_EPI = false, bool SP2 = false>
; __device__ __forceinline__ void gemm_phase(PG8_LAS unsigned char* lds, const Gemm g, const Sched& S, const Epi& E) {
;     ...
;     if constexpr (SP2) {
;         PG8_STAGE(PG8_SB(0, 0), cB, voffB); PG8_STAGE(PG8_SB(0, 1), cB + hstep, voffB); PG8_STAGE(PG8_SA(0, 0), cA, voffA); PG8_STAGE(PG8_SA(0, 1), cA + hstep, voffA);
;         if (wr == 1) PG8_BAR;
;         PG8_WAIT_V(2); PG8_BAR;
;         PG8_STAGE(PG8_SB(1, 0), cB + kstep, voffB); PG8_STAGE(PG8_SA(1, 0), cA + kstep, voffA); PG8_STAGE(PG8_SB(1, 1), cB + hstep + kstep, voffB);
;         PG8_WAIT_V(6); PG8_BAR;
.LBB0_342:
	s_lshl_b32 s1, s1, 5
	s_mov_b64 s[6:7], 0x80
	s_and_b32 s1, s1, 0x60
	s_add_i32 m0, s24, 0x18000
	v_lshl_add_u64 v[6:7], v[6:7], 0, s[6:7]
	s_lshl_b32 s38, s9, 13
	s_lshl_b32 s39, s1, 7
	global_load_lds_dwordx4 v[6:7], off
	v_lshl_add_u64 v[4:5], v[4:5], 0, s[6:7]
	s_add_i32 m0, s24, 0x1a000
	s_add_i32 s56, s24, 0x8000
	s_add_i32 s57, s24, 0xa000
	global_load_lds_dwordx4 v[4:5], off
	v_lshl_add_u64 v[0:1], v[0:1], 0, s[6:7]
	s_mov_b32 m0, s56
	s_add_u32 s26, s48, 0x40080
	global_load_lds_dwordx4 v[0:1], off
	v_lshl_add_u64 v[0:1], v[2:3], 0, s[6:7]
	s_mov_b32 m0, s57
	s_addc_u32 s27, s49, 0
	global_load_lds_dwordx4 v[0:1], off
	s_add_i32 m0, s24, 0x1c000
	v_lshl_add_u64 v[0:1], s[26:27], 0, v[130:131]
	global_load_lds_dwordx4 v[0:1], off
	v_lshl_add_u64 v[0:1], s[26:27], 0, v[134:135]
	s_add_i32 m0, s24, 0x1e000
	s_cmpk_lt_u32 s8, 0x100
	global_load_lds_dwordx4 v[0:1], off
	s_waitcnt vmcnt(8)
	s_barrier
	v_lshrrev_b32_e32 v1, 1, v8
	v_and_b32_e32 v1, 24, v1
	v_and_b32_e32 v0, 15, v8
	v_lshlrev_b32_e32 v2, 1, v1
	v_lshl_or_b32 v148, s9, 6, v0
	v_lshl_or_b32 v0, v0, 6, v2
	v_lshlrev_b32_e32 v2, 2, v8
	v_and_b32_e32 v2, 32, v2
	v_bitop3_b32 v3, v0, s38, v2 bitop3:0xde
	v_bitop3_b32 v149, v0, s39, v2 bitop3:0xde
	v_lshlrev_b32_e32 v0, 14, v9
	v_and_b32_e32 v0, 0xffff8000, v0
	v_or_b32_e32 v150, s1, v1
	v_lshl_add_u32 v0, v10, 11, v0
	v_and_b32_e32 v1, 1, v9
	v_lshl_or_b32 v0, v1, 6, v0
	v_lshl_add_u32 v136, v11, 1, v0
	v_lshlrev_b32_e32 v0, 14, v12
	v_and_b32_e32 v0, 0xffff8000, v0
	s_waitcnt vmcnt(6)
	v_lshl_add_u32 v0, v13, 11, v0
	v_and_b32_e32 v1, 1, v12
	s_cselect_b64 s[8:9], -1, 0
	v_lshl_or_b32 v0, v1, 6, v0
	s_add_i32 s60, 0, 0x10000
	s_add_i32 s61, 0, 0x14000
	s_sext_i32_i8 s64, s0
	s_ashr_i32 s58, s86, 31
	s_mov_b32 s59, s86
	v_mov_b32_e32 v137, v131
	v_lshl_add_u32 v138, v14, 1, v0
	v_mov_b32_e32 v139, v131
	v_mov_b64_e32 v[140:141], 0x100
	v_mov_b64_e32 v[142:143], 0xff
	v_add_u32_e32 v151, s60, v149
	v_add_u32_e32 v152, s61, v149
	v_add_u32_e32 v153, 0, v3
	s_barrier
	s_branch .LBB0_345

; #define PG8_STAGE(bufoff, gbase, voff) do { _Pragma("unroll") for (int _i = 0; _i < 2; ++_i) \
;         __builtin_amdgcn_global_load_lds((const unsigned*)((const char*)(gbase) + (voff)[_i]), (PG8_LAS unsigned*)(lds + (bufoff) + ldsw + _i * 8192), 16, 0, 0); } while (0)
; #define PG8_WAIT_V(n) asm volatile("s_waitcnt vmcnt(" #n ")" ::: "memory")
; #define PG8_BAR __builtin_amdgcn_s_barrier()
; template <class Epi, class Sched, bool ALIGN_EPI = false, bool SP2 = false>
; __device__ __forceinline__ void gemm_phase(PG8_LAS unsigned char* lds, const Gemm g, const Sched& S, const Epi& E) {
;     ...
;     if constexpr (SP2) {
;         PG8_STAGE(PG8_SB(0, 0), cB, voffB); PG8_STAGE(PG8_SB(0, 1), cB + hstep, voffB); PG8_STAGE(PG8_SA(0, 0), cA, voffA); PG8_STAGE(PG8_SA(0, 1), cA + hstep, voffA);
;         if (wr == 1) PG8_BAR;
;         PG8_WAIT_V(2); PG8_BAR;
;         PG8_STAGE(PG8_SB(1, 0), cB + kstep, voffB); PG8_STAGE(PG8_SA(1, 0), cA + kstep, voffA); PG8_STAGE(PG8_SB(1, 1), cB + hstep + kstep, voffB);
;         PG8_WAIT_V(6); PG8_BAR;
.LBB0_368:
	s_mov_b64 s[38:39], 0x80
	s_and_b32 s1, s1, 3
	s_add_i32 m0, s25, 0x18000
	v_lshl_add_u64 v[6:7], v[6:7], 0, s[38:39]
	s_lshl_b32 s7, s8, 13
	s_lshl_b32 s9, s1, 12
	global_load_lds_dwordx4 v[6:7], off
	v_lshl_add_u64 v[4:5], v[4:5], 0, s[38:39]
	s_add_i32 m0, s25, 0x1a000
	s_add_i32 s63, s25, 0x8000
	s_add_i32 s64, s25, 0xa000
	global_load_lds_dwordx4 v[4:5], off
	v_lshl_add_u64 v[0:1], v[0:1], 0, s[38:39]
	s_mov_b32 m0, s63
	s_add_u32 s4, s58, 0x30080
	global_load_lds_dwordx4 v[0:1], off
	v_lshl_add_u64 v[0:1], v[2:3], 0, s[38:39]
	s_mov_b32 m0, s64
	s_addc_u32 s5, s59, 0
	global_load_lds_dwordx4 v[0:1], off
	s_add_i32 m0, s25, 0x1c000
	v_lshl_add_u64 v[0:1], s[4:5], 0, v[186:187]
	global_load_lds_dwordx4 v[0:1], off
	v_lshl_add_u64 v[0:1], s[4:5], 0, v[190:191]
	s_add_i32 m0, s25, 0x1e000
	s_cmpk_lt_u32 s6, 0x100
	global_load_lds_dwordx4 v[0:1], off
	s_waitcnt vmcnt(8)
	s_barrier
	v_and_b32_e32 v0, 15, v8
	v_bfe_u32 v1, v8, 4, 2
	v_lshlrev_b32_e32 v3, 4, v1
	v_lshlrev_b32_e32 v4, 2, v0
	v_lshl_or_b32 v195, s8, 6, v0
	v_lshl_or_b32 v3, v0, 6, v3
	v_and_b32_e32 v0, 32, v4
	v_lshlrev_b32_e32 v2, 3, v1
	v_bitop3_b32 v5, v3, s7, v0 bitop3:0xde
	v_bitop3_b32 v227, v3, s9, v0 bitop3:0xde
	s_cselect_b64 s[40:41], -1, 0
	s_cmp_lt_u32 s1, 2
	v_lshlrev_b32_e32 v0, 2, v1
	v_lshl_or_b32 v194, s1, 4, v0
	s_cselect_b64 s[4:5], -1, 0
	s_lshl_b32 s8, s8, 11
	v_lshl_or_b32 v0, s1, 5, v2
	v_cmp_eq_u32_e64 s[6:7], 0, v1
	s_lshl_b32 s9, s1, 9
	s_add_i32 s1, s8, 0
	v_lshlrev_b32_e32 v192, 2, v0
	v_cndmask_b32_e64 v1, 0, v194, s[4:5]
	s_add_i32 s1, s1, 0x20000
	v_lshl_add_u64 v[196:197], s[42:43], 0, v[192:193]
	v_lshlrev_b32_e32 v192, 2, v1
	s_add_i32 s8, s1, s9
	v_lshl_add_u64 v[198:199], s[42:43], 0, v[192:193]
	v_lshlrev_b32_e32 v192, 2, v194
	v_add_u32_e32 v228, s8, v4
	v_lshl_add_u64 v[2:3], s[30:31], 0, v[192:193]
	s_mov_b64 s[8:9], 0x15600000
	v_lshl_add_u64 v[200:201], v[2:3], 0, s[8:9]
	s_mov_b64 s[8:9], 0x15700000
	v_lshl_add_u64 v[202:203], v[2:3], 0, s[8:9]
	v_add_u32_e32 v229, s1, v4
	v_lshrrev_b32_e32 v1, 1, v9
	v_mul_lo_u32 v2, v11, s0
	s_movk_i32 s1, 0x3000
	v_mad_u64_u32 v[2:3], s[8:9], v1, s1, v[2:3]
	v_or_b32_e32 v1, v2, v10
	v_add_lshl_u32 v192, v1, v12, 1
	v_lshrrev_b32_e32 v1, 1, v13
	v_mul_lo_u32 v2, v14, s0
	v_mad_u64_u32 v[2:3], s[0:1], v1, s1, v[2:3]
	s_mov_b64 s[46:47], 0x30080
	s_waitcnt vmcnt(6)
	v_or_b32_e32 v1, v2, v15
	v_lshl_add_u64 v[204:205], v[192:193], 0, s[46:47]
	v_add_lshl_u32 v192, v1, v16, 1
	s_add_i32 s68, 0, 0x10000
	s_add_i32 s69, 0, 0x14000
	s_ashr_i32 s65, s86, 31
	s_mov_b32 s66, s86
	s_ashr_i32 s67, s2, 31
	v_lshl_add_u64 v[206:207], v[192:193], 0, s[46:47]
	v_mov_b64_e32 v[208:209], 0x200
	v_mov_b64_e32 v[210:211], 0x1ff
	v_add_u32_e32 v230, s68, v227
	v_add_u32_e32 v231, s69, v227
	v_add_u32_e32 v232, 0, v5
	v_mov_b32_e32 v233, 0x358637bd
	s_mov_b32 s70, 0x800000
	s_movk_i32 s71, 0x1800
	v_lshlrev_b32_e32 v192, 1, v0
	s_mov_b64 s[42:43], 0x5000
	s_mov_b64 s[46:47], 0x5800
	s_barrier
	s_branch .LBB0_371

; #define PG8_STAGE(bufoff, gbase, voff) do { _Pragma("unroll") for (int _i = 0; _i < 2; ++_i) \
;         __builtin_amdgcn_global_load_lds((const unsigned*)((const char*)(gbase) + (voff)[_i]), (PG8_LAS unsigned*)(lds + (bufoff) + ldsw + _i * 8192), 16, 0, 0); } while (0)
; #define PG8_WAIT_V(n) asm volatile("s_waitcnt vmcnt(" #n ")" ::: "memory")
; #define PG8_BAR __builtin_amdgcn_s_barrier()
; template <class Epi, class Sched, bool ALIGN_EPI = false, bool SP2 = false>
; __device__ __forceinline__ void gemm_phase(PG8_LAS unsigned char* lds, const Gemm g, const Sched& S, const Epi& E) {
;     ...
;     if constexpr (SP2) {
;         PG8_STAGE(PG8_SB(0, 0), cB, voffB); PG8_STAGE(PG8_SB(0, 1), cB + hstep, voffB); PG8_STAGE(PG8_SA(0, 0), cA, voffA); PG8_STAGE(PG8_SA(0, 1), cA + hstep, voffA);
;         if (wr == 1) PG8_BAR;
;         PG8_WAIT_V(2); PG8_BAR;
;         PG8_STAGE(PG8_SB(1, 0), cB + kstep, voffB); PG8_STAGE(PG8_SA(1, 0), cA + kstep, voffA); PG8_STAGE(PG8_SB(1, 1), cB + hstep + kstep, voffB);
;         PG8_WAIT_V(6); PG8_BAR;
.LBB0_434:
	s_and_b32 s40, s0, 3
	s_lshl_b32 s26, s5, 13
	s_lshl_b32 s27, s40, 12
	s_add_u32 s10, s30, 0x15a00000
	s_mov_b64 s[18:19], 0x80
	s_addc_u32 s11, s31, 0
	s_add_i32 m0, s25, 0x18000
	v_lshl_add_u64 v[6:7], v[6:7], 0, s[18:19]
	global_load_lds_dwordx4 v[6:7], off
	v_lshl_add_u64 v[4:5], v[4:5], 0, s[18:19]
	s_add_i32 m0, s25, 0x1a000
	s_add_i32 s59, s25, 0x8000
	s_add_i32 s60, s25, 0xa000
	global_load_lds_dwordx4 v[4:5], off
	v_lshl_add_u64 v[0:1], v[0:1], 0, s[18:19]
	s_mov_b32 m0, s59
	s_add_u32 s0, s54, 0x20080
	global_load_lds_dwordx4 v[0:1], off
	v_lshl_add_u64 v[0:1], v[2:3], 0, s[18:19]
	s_mov_b32 m0, s60
	s_addc_u32 s1, s55, 0
	global_load_lds_dwordx4 v[0:1], off
	s_add_i32 m0, s25, 0x1c000
	v_lshl_add_u64 v[0:1], s[0:1], 0, v[158:159]
	global_load_lds_dwordx4 v[0:1], off
	v_lshl_add_u64 v[0:1], s[0:1], 0, v[162:163]
	s_add_i32 m0, s25, 0x1e000
	s_cmpk_lt_u32 s4, 0x100
	global_load_lds_dwordx4 v[0:1], off
	s_waitcnt vmcnt(8)
	s_barrier
	v_and_b32_e32 v0, 15, v8
	v_bfe_u32 v1, v8, 4, 2
	v_lshlrev_b32_e32 v3, 4, v1
	v_lshlrev_b32_e32 v6, 2, v0
	v_lshl_or_b32 v196, s5, 6, v0
	v_lshlrev_b32_e32 v2, 3, v1
	v_lshl_or_b32 v3, v0, 6, v3
	v_and_b32_e32 v0, 32, v6
	v_cmp_eq_u32_e64 s[0:1], 0, v1
	v_lshlrev_b32_e32 v1, 2, v1
	v_bitop3_b32 v7, v3, s26, v0 bitop3:0xde
	v_bitop3_b32 v197, v3, s27, v0 bitop3:0xde
	v_lshl_or_b32 v0, s40, 5, v2
	v_lshl_or_b32 v2, s40, 4, v1
	v_lshlrev_b32_e32 v1, 13, v9
	v_and_b32_e32 v1, 0xffffc000, v1
	v_lshl_add_u32 v1, v10, 10, v1
	v_and_b32_e32 v3, 1, v9
	s_cselect_b64 s[26:27], -1, 0
	s_lshl_b32 s4, s5, 11
	v_lshl_or_b32 v1, v3, 6, v1
	s_add_i32 s4, s4, 0
	v_lshl_add_u32 v170, v11, 1, v1
	v_lshlrev_b32_e32 v1, 13, v12
	s_lshl_b32 s5, s40, 9
	s_add_i32 s40, s4, 0x20000
	v_lshlrev_b32_e32 v164, 2, v0
	v_and_b32_e32 v1, 0xffffc000, v1
	s_waitcnt vmcnt(6)
	s_add_i32 s4, s40, s5
	v_lshl_add_u64 v[166:167], s[44:45], 0, v[164:165]
	v_lshlrev_b32_e32 v164, 2, v2
	v_lshl_add_u32 v1, v13, 10, v1
	v_and_b32_e32 v3, 1, v12
	v_add_u32_e32 v198, s4, v6
	v_lshl_add_u64 v[4:5], s[30:31], 0, v[164:165]
	s_mov_b64 s[4:5], 0x15800000
	v_lshl_or_b32 v1, v3, 6, v1
	s_add_i32 s64, 0, 0x10000
	s_add_i32 s65, 0, 0x14000
	s_ashr_i32 s61, s86, 31
	s_mov_b32 s62, s86
	s_ashr_i32 s63, s2, 31
	v_lshl_add_u64 v[168:169], v[4:5], 0, s[4:5]
	v_add_u32_e32 v199, s40, v6
	v_mov_b32_e32 v171, v165
	v_lshl_add_u32 v172, v14, 1, v1
	v_mov_b32_e32 v173, v165
	v_mov_b64_e32 v[174:175], 0x200
	v_mov_b64_e32 v[176:177], 0x1ff
	v_add_u32_e32 v200, s64, v197
	v_add_u32_e32 v201, s65, v197
	v_add_u32_e32 v202, 0, v7
	v_mov_b32_e32 v203, 0x358637bd
	s_mov_b32 s66, 0x800000
	s_movk_i32 s67, 0x1800
	v_lshlrev_b32_e32 v164, 1, v0
	v_lshlrev_b32_e32 v178, 1, v2
	s_barrier
	s_branch .LBB0_437

; #define PG8_STAGE(bufoff, gbase, voff) do { _Pragma("unroll") for (int _i = 0; _i < 2; ++_i) \
;         __builtin_amdgcn_global_load_lds((const unsigned*)((const char*)(gbase) + (voff)[_i]), (PG8_LAS unsigned*)(lds + (bufoff) + ldsw + _i * 8192), 16, 0, 0); } while (0)
; #define PG8_WAIT_V(n) asm volatile("s_waitcnt vmcnt(" #n ")" ::: "memory")
; #define PG8_BAR __builtin_amdgcn_s_barrier()
; template <class Epi, class Sched, bool ALIGN_EPI = false, bool SP2 = false>
; __device__ __forceinline__ void gemm_phase(PG8_LAS unsigned char* lds, const Gemm g, const Sched& S, const Epi& E) {
;     ...
;     if constexpr (SP2) {
;         PG8_STAGE(PG8_SB(0, 0), cB, voffB); PG8_STAGE(PG8_SB(0, 1), cB + hstep, voffB); PG8_STAGE(PG8_SA(0, 0), cA, voffA); PG8_STAGE(PG8_SA(0, 1), cA + hstep, voffA);
;         if (wr == 1) PG8_BAR;
;         PG8_WAIT_V(2); PG8_BAR;
;         PG8_STAGE(PG8_SB(1, 0), cB + kstep, voffB); PG8_STAGE(PG8_SA(1, 0), cA + kstep, voffA); PG8_STAGE(PG8_SB(1, 1), cB + hstep + kstep, voffB);
;         PG8_WAIT_V(6); PG8_BAR;
.LBB0_622:
	s_lshl_b32 s5, s5, 5
	s_mov_b64 s[8:9], 0x80
	s_and_b32 s5, s5, 0x60
	s_add_i32 m0, s13, 0x18000
	v_lshl_add_u64 v[6:7], v[6:7], 0, s[8:9]
	s_lshl_b32 s1, s10, 13
	s_lshl_b32 s11, s5, 7
	global_load_lds_dwordx4 v[6:7], off
	v_lshl_add_u64 v[4:5], v[4:5], 0, s[8:9]
	s_add_i32 m0, s13, 0x1a000
	s_add_i32 s33, s13, 0x8000
	s_add_i32 s34, s13, 0xa000
	global_load_lds_dwordx4 v[4:5], off
	v_lshl_add_u64 v[0:1], v[0:1], 0, s[8:9]
	s_mov_b32 m0, s33
	s_add_u32 s18, s46, 0x80080
	global_load_lds_dwordx4 v[0:1], off
	v_lshl_add_u64 v[0:1], v[2:3], 0, s[8:9]
	s_mov_b32 m0, s34
	s_addc_u32 s19, s47, 0
	global_load_lds_dwordx4 v[0:1], off
	s_add_i32 m0, s13, 0x1c000
	v_lshl_add_u64 v[0:1], s[18:19], 0, v[194:195]
	global_load_lds_dwordx4 v[0:1], off
	v_lshl_add_u64 v[0:1], s[18:19], 0, v[198:199]
	s_add_i32 m0, s13, 0x1e000
	s_cmpk_lt_u32 s4, 0x100
	global_load_lds_dwordx4 v[0:1], off
	s_waitcnt vmcnt(8)
	s_barrier
	v_lshrrev_b32_e32 v1, 1, v8
	v_and_b32_e32 v1, 24, v1
	v_and_b32_e32 v0, 15, v8
	v_lshlrev_b32_e32 v2, 1, v1
	v_lshl_or_b32 v220, s10, 6, v0
	v_lshl_or_b32 v0, v0, 6, v2
	v_lshlrev_b32_e32 v2, 2, v8
	v_and_b32_e32 v2, 32, v2
	v_bitop3_b32 v3, v0, s1, v2 bitop3:0xde
	v_bitop3_b32 v221, v0, s11, v2 bitop3:0xde
	v_lshlrev_b32_e32 v0, 15, v9
	v_and_b32_e32 v0, 0xffff0000, v0
	v_or_b32_e32 v222, s5, v1
	v_lshl_add_u32 v0, v10, 12, v0
	v_and_b32_e32 v1, 1, v9
	s_cselect_b64 s[10:11], -1, 0
	s_ashr_i32 s35, s86, 31
	s_ashr_i32 s55, s2, 31
	v_lshl_or_b32 v0, v1, 6, v0
	s_add_u32 s18, s30, 0xa601000
	v_lshl_add_u32 v200, v11, 1, v0
	v_lshlrev_b32_e32 v0, 15, v12
	s_addc_u32 s19, s31, 0
	v_and_b32_e32 v0, 0xffff0000, v0
	s_waitcnt vmcnt(6)
	s_cmp_lg_u64 s[30:31], 0
	v_lshl_add_u32 v0, v13, 12, v0
	v_and_b32_e32 v1, 1, v12
	s_cselect_b64 s[20:21], -1, 0
	v_lshl_or_b32 v0, v1, 6, v0
	s_add_i32 s56, 0, 0x10000
	s_add_i32 s57, 0, 0x14000
	s_mov_b32 s54, s86
	v_mov_b32_e32 v201, v195
	v_lshl_add_u32 v202, v14, 1, v0
	v_mov_b32_e32 v203, v195
	v_mov_b64_e32 v[204:205], 0x100
	v_mov_b64_e32 v[206:207], 0xff
	v_add_u32_e32 v223, s56, v221
	v_add_u32_e32 v224, s57, v221
	v_add_u32_e32 v225, 0, v3
	s_barrier
	s_branch .LBB0_625

; #define PG8_STAGE(bufoff, gbase, voff) do { _Pragma("unroll") for (int _i = 0; _i < 2; ++_i) \
;         __builtin_amdgcn_global_load_lds((const unsigned*)((const char*)(gbase) + (voff)[_i]), (PG8_LAS unsigned*)(lds + (bufoff) + ldsw + _i * 8192), 16, 0, 0); } while (0)
; #define PG8_WAIT_V(n) asm volatile("s_waitcnt vmcnt(" #n ")" ::: "memory")
; #define PG8_BAR __builtin_amdgcn_s_barrier()
; template <class Epi, class Sched, bool ALIGN_EPI = false, bool SP2 = false>
; __device__ __forceinline__ void gemm_phase(PG8_LAS unsigned char* lds, const Gemm g, const Sched& S, const Epi& E) {
;     ...
;     if constexpr (SP2) {
;         PG8_STAGE(PG8_SB(0, 0), cB, voffB); PG8_STAGE(PG8_SB(0, 1), cB + hstep, voffB); PG8_STAGE(PG8_SA(0, 0), cA, voffA); PG8_STAGE(PG8_SA(0, 1), cA + hstep, voffA);
;         if (wr == 1) PG8_BAR;
;         PG8_WAIT_V(2); PG8_BAR;
;         PG8_STAGE(PG8_SB(1, 0), cB + kstep, voffB); PG8_STAGE(PG8_SA(1, 0), cA + kstep, voffA); PG8_STAGE(PG8_SB(1, 1), cB + hstep + kstep, voffB);
;         PG8_WAIT_V(6); PG8_BAR;
.LBB0_793:
	s_lshl_b32 s6, s6, 5
	s_mov_b64 s[8:9], 0x80
	s_and_b32 s12, s6, 0x60
	s_add_i32 m0, s24, 0x18000
	v_lshl_add_u64 v[6:7], v[6:7], 0, s[8:9]
	s_lshl_b32 s10, s5, 13
	s_lshl_b32 s11, s12, 7
	global_load_lds_dwordx4 v[6:7], off
	v_lshl_add_u64 v[4:5], v[4:5], 0, s[8:9]
	s_add_i32 m0, s24, 0x1a000
	s_add_i32 s34, s24, 0x8000
	s_add_i32 s35, s24, 0xa000
	global_load_lds_dwordx4 v[4:5], off
	v_lshl_add_u64 v[0:1], v[0:1], 0, s[8:9]
	s_mov_b32 m0, s34
	s_add_u32 s6, s44, 0x80080
	global_load_lds_dwordx4 v[0:1], off
	v_lshl_add_u64 v[0:1], v[2:3], 0, s[8:9]
	s_mov_b32 m0, s35
	s_addc_u32 s7, s45, 0
	global_load_lds_dwordx4 v[0:1], off
	s_add_i32 m0, s24, 0x1c000
	v_lshl_add_u64 v[0:1], s[6:7], 0, v[176:177]
	global_load_lds_dwordx4 v[0:1], off
	v_lshl_add_u64 v[0:1], s[6:7], 0, v[178:179]
	s_add_i32 m0, s24, 0x1e000
	s_cmpk_lt_u32 s4, 0x100
	global_load_lds_dwordx4 v[0:1], off
	s_waitcnt vmcnt(8)
	s_barrier
	v_bfe_u32 v1, v8, 4, 2
	v_and_b32_e32 v0, 15, v8
	v_lshlrev_b32_e32 v2, 4, v1
	v_lshl_or_b32 v200, s5, 6, v0
	v_lshl_or_b32 v0, v0, 6, v2
	v_lshlrev_b32_e32 v2, 2, v8
	v_and_b32_e32 v2, 32, v2
	v_bitop3_b32 v3, v0, s10, v2 bitop3:0xde
	v_bitop3_b32 v201, v0, s11, v2 bitop3:0xde
	v_lshlrev_b32_e32 v0, 15, v9
	v_and_b32_e32 v0, 0xffff0000, v0
	v_cmp_eq_u32_e64 s[4:5], 0, v1
	v_lshl_or_b32 v202, v1, 2, s12
	v_lshl_add_u32 v0, v10, 12, v0
	v_and_b32_e32 v1, 1, v9
	v_lshl_or_b32 v0, v1, 6, v0
	v_lshl_add_u32 v180, v11, 1, v0
	v_lshlrev_b32_e32 v0, 15, v12
	v_and_b32_e32 v0, 0xffff0000, v0
	s_waitcnt vmcnt(6)
	v_lshl_add_u32 v0, v13, 12, v0
	v_and_b32_e32 v1, 1, v12
	s_cselect_b64 s[10:11], -1, 0
	v_lshl_or_b32 v0, v1, 6, v0
	s_add_i32 s55, 0, 0x10000
	s_add_i32 s56, 0, 0x14000
	s_ashr_i32 s48, s86, 31
	s_mov_b32 s49, s86
	s_ashr_i32 s54, s2, 31
	v_mov_b32_e32 v181, v177
	v_lshl_add_u32 v182, v14, 1, v0
	v_mov_b32_e32 v183, v177
	v_mov_b64_e32 v[184:185], 0x100
	v_mov_b64_e32 v[186:187], 0xff
	v_add_u32_e32 v203, s55, v201
	v_add_u32_e32 v204, s56, v201
	v_add_u32_e32 v205, 0, v3
	s_barrier
	s_branch .LBB0_796

; #define PG8_STAGE(bufoff, gbase, voff) do { _Pragma("unroll") for (int _i = 0; _i < 2; ++_i) \
;         __builtin_amdgcn_global_load_lds((const unsigned*)((const char*)(gbase) + (voff)[_i]), (PG8_LAS unsigned*)(lds + (bufoff) + ldsw + _i * 8192), 16, 0, 0); } while (0)
; #define PG8_WAIT_V(n) asm volatile("s_waitcnt vmcnt(" #n ")" ::: "memory")
; #define PG8_BAR __builtin_amdgcn_s_barrier()
; template <class Epi, class Sched, bool ALIGN_EPI = false, bool SP2 = false>
; __device__ __forceinline__ void gemm_phase(PG8_LAS unsigned char* lds, const Gemm g, const Sched& S, const Epi& E) {
;     ...
;     if constexpr (SP2) {
;         PG8_STAGE(PG8_SB(0, 0), cB, voffB); PG8_STAGE(PG8_SB(0, 1), cB + hstep, voffB); PG8_STAGE(PG8_SA(0, 0), cA, voffA); PG8_STAGE(PG8_SA(0, 1), cA + hstep, voffA);
;         if (wr == 1) PG8_BAR;
;         PG8_WAIT_V(2); PG8_BAR;
;         PG8_STAGE(PG8_SB(1, 0), cB + kstep, voffB); PG8_STAGE(PG8_SA(1, 0), cA + kstep, voffA); PG8_STAGE(PG8_SB(1, 1), cB + hstep + kstep, voffB);
;         PG8_WAIT_V(6); PG8_BAR;
.LBB0_881:
	s_lshl_b32 s4, s4, 5
	s_mov_b64 s[44:45], 0x80
	s_and_b32 s7, s4, 0x60
	s_add_i32 m0, s94, 0x18000
	v_lshl_add_u64 v[6:7], v[6:7], 0, s[44:45]
	s_lshl_b32 s6, s92, 13
	s_lshl_b32 s8, s7, 7
	global_load_lds_dwordx4 v[6:7], off
	v_lshl_add_u64 v[4:5], v[4:5], 0, s[44:45]
	s_add_i32 m0, s94, 0x1a000
	s_add_i32 s91, s94, 0x8000
	s_add_i32 s24, s94, 0xa000
	global_load_lds_dwordx4 v[4:5], off
	v_lshl_add_u64 v[2:3], v[2:3], 0, s[44:45]
	s_mov_b32 m0, s91
	s_add_u32 s4, s66, 0x80080
	global_load_lds_dwordx4 v[2:3], off
	v_lshl_add_u64 v[0:1], v[0:1], 0, s[44:45]
	s_mov_b32 m0, s24
	s_addc_u32 s5, s67, 0
	global_load_lds_dwordx4 v[0:1], off
	s_add_i32 m0, s94, 0x1c000
	v_lshl_add_u64 v[0:1], s[4:5], 0, v[178:179]
	global_load_lds_dwordx4 v[0:1], off
	v_lshl_add_u64 v[0:1], s[4:5], 0, v[182:183]
	s_add_i32 m0, s94, 0x1e000
	v_lshrrev_b32_e32 v16, 1, v9
	global_load_lds_dwordx4 v[0:1], off
	s_waitcnt vmcnt(8)
	s_barrier
	v_and_b32_e32 v16, 24, v16
	s_cmpk_lt_u32 s3, 0x100
	v_and_b32_e32 v15, 15, v9
	v_lshlrev_b32_e32 v17, 1, v16
	v_lshlrev_b32_e32 v0, 2, v9
	s_cselect_b64 s[4:5], -1, 0
	v_lshl_or_b32 v17, v15, 6, v17
	v_and_b32_e32 v0, 32, v0
	v_writelane_b32 v254, s4, 13
	v_bitop3_b32 v1, v17, s6, v0 bitop3:0xde
	v_or_b32_e32 v210, s7, v16
	v_writelane_b32 v254, s5, 14
	v_cmp_lt_u32_e64 s[4:5], 13, v15
	v_cmp_gt_u32_e64 s[6:7], 2, v15
	v_lshl_or_b32 v208, s92, 6, v15
	v_writelane_b32 v254, s4, 20
	v_cndmask_b32_e64 v211, 0, 1, s[0:1]
	s_and_b64 s[48:49], s[0:1], s[6:7]
	s_movk_i32 s1, 0xff81
	v_writelane_b32 v254, s5, 21
	v_cmp_lt_i32_e64 s[4:5], s1, v208
	s_movk_i32 s1, 0xff71
	v_cmp_lt_i32_e64 s[12:13], s1, v208
	s_movk_i32 s1, 0xff61
	s_add_i32 s0, 0, 0x20000
	v_writelane_b32 v254, s12, 22
	s_cmp_gt_i32 s92, -1
	s_cselect_b64 s[52:53], -1, 0
	v_writelane_b32 v254, s13, 23
	v_cmp_lt_i32_e64 s[12:13], s1, v208
	v_bitop3_b32 v209, v17, s8, v0 bitop3:0xde
	v_lshlrev_b32_e32 v0, 10, v15
	v_writelane_b32 v254, s12, 24
	v_lshl_add_u32 v2, s92, 11, v0
	v_lshlrev_b32_e32 v3, 11, v211
	v_writelane_b32 v254, s13, 25
	s_movk_i32 s1, 0xff51
	v_readlane_b32 s26, v254, 11
	v_readlane_b32 s27, v254, 12
	v_readlane_b32 s56, v254, 0
	s_ashr_i32 s25, s26, 31
	s_ashr_i32 s27, s2, 31
	v_readlane_b32 s58, v254, 2
	v_readlane_b32 s59, v254, 3
	s_add_u32 s54, s58, 0xb000
	s_addc_u32 s55, s59, 0
	v_readlane_b32 s57, v254, 1
	s_add_u32 s56, s58, 0x16000
	v_add_u32_e32 v2, 0xffffc800, v2
	v_add_u32_e32 v3, s0, v3
	v_cmp_lt_i32_e64 s[20:21], s1, v208
	s_addc_u32 s57, s59, 0
	v_lshlrev_b32_e32 v4, 2, v210
	s_add_i32 s1, 0, 0x21000
	v_add3_u32 v215, s0, v2, v4
	v_add3_u32 v216, s1, v2, v4
	v_add_u32_e32 v2, 0xfffff800, v3
	s_add_i32 s0, s0, s22
	v_add_u32_e32 v217, v2, v4
	v_add_u32_e32 v219, s0, v4
	v_add_u32_e32 v218, v217, v0
	v_add_u32_e32 v220, v219, v0
	v_lshlrev_b32_e32 v0, 15, v8
	v_and_b32_e32 v0, 0xffff0000, v0
	v_lshl_add_u32 v0, v10, 12, v0
	v_and_b32_e32 v2, 1, v8
	v_lshl_or_b32 v0, v2, 6, v0
	v_lshl_add_u32 v184, v11, 1, v0
	v_lshlrev_b32_e32 v0, 15, v12
	v_and_b32_e32 v0, 0xffff0000, v0
	s_waitcnt vmcnt(6)
	v_lshl_add_u32 v0, v13, 12, v0
	v_and_b32_e32 v2, 1, v12
	v_lshl_or_b32 v0, v2, 6, v0
	s_add_i32 s90, 0, 0x10000
	s_add_i32 s3, 0, 0x14000
	v_cmp_eq_u32_e64 s[8:9], 0, v15
	v_cmp_lt_u32_e64 s[10:11], 1, v15
	v_cmp_lt_i32_e64 s[46:47], 1, v208
	v_or_b32_e32 v212, 16, v208
	v_or_b32_e32 v213, 32, v208
	v_or_b32_e32 v214, 48, v208
	v_mov_b32_e32 v185, v179
	v_lshl_add_u32 v186, v14, 1, v0
	v_mov_b32_e32 v187, v179
	v_mov_b64_e32 v[188:189], 0x5d8
	v_mov_b64_e32 v[190:191], 0x5d7
	v_add_u32_e32 v221, s90, v209
	v_add_u32_e32 v222, s3, v209
	v_add_u32_e32 v223, 0, v1
	s_movk_i32 s34, 0x5000
	v_mov_b32_e32 v224, 0x358637bd
	s_mov_b32 s35, 0x800000
	s_movk_i32 s68, 0x1000
	s_movk_i32 s69, 0x2c00
	v_mov_b32_e32 v225, 0xfff
	s_barrier
	v_readlane_b32 s60, v254, 4
	v_readlane_b32 s61, v254, 5
	v_readlane_b32 s62, v254, 6
	v_readlane_b32 s63, v254, 7
	s_branch .LBB0_884

; #define PG8_STAGE(bufoff, gbase, voff) do { _Pragma("unroll") for (int _i = 0; _i < 2; ++_i) \
;         __builtin_amdgcn_global_load_lds((const unsigned*)((const char*)(gbase) + (voff)[_i]), (PG8_LAS unsigned*)(lds + (bufoff) + ldsw + _i * 8192), 16, 0, 0); } while (0)
; #define PG8_WAIT_V(n) asm volatile("s_waitcnt vmcnt(" #n ")" ::: "memory")
; #define PG8_BAR __builtin_amdgcn_s_barrier()
; template <class Epi, class Sched, bool ALIGN_EPI = false, bool SP2 = false>
; __device__ __forceinline__ void gemm_phase(PG8_LAS unsigned char* lds, const Gemm g, const Sched& S, const Epi& E) {
;     ...
;     if constexpr (SP2) {
;         PG8_STAGE(PG8_SB(0, 0), cB, voffB); PG8_STAGE(PG8_SB(0, 1), cB + hstep, voffB); PG8_STAGE(PG8_SA(0, 0), cA, voffA); PG8_STAGE(PG8_SA(0, 1), cA + hstep, voffA);
;         if (wr == 1) PG8_BAR;
;         PG8_WAIT_V(2); PG8_BAR;
;         PG8_STAGE(PG8_SB(1, 0), cB + kstep, voffB); PG8_STAGE(PG8_SA(1, 0), cA + kstep, voffA); PG8_STAGE(PG8_SB(1, 1), cB + hstep + kstep, voffB);
;         PG8_WAIT_V(6); PG8_BAR;
.LBB0_1084:
	s_lshl_b32 s12, s12, 5
	s_and_b32 s20, s12, 0x60
	s_mov_b64 s[12:13], 0x80
	s_add_i32 m0, s34, 0x18000
	v_lshl_add_u64 v[6:7], v[6:7], 0, s[12:13]
	s_lshl_b32 s17, s1, 13
	s_lshl_b32 s18, s20, 7
	global_load_lds_dwordx4 v[6:7], off
	v_lshl_add_u64 v[4:5], v[4:5], 0, s[12:13]
	s_add_i32 m0, s34, 0x1a000
	s_add_i32 s43, s34, 0x8000
	s_add_i32 s44, s34, 0xa000
	global_load_lds_dwordx4 v[4:5], off
	v_lshl_add_u64 v[0:1], v[0:1], 0, s[12:13]
	s_mov_b32 m0, s43
	s_add_u32 s14, s26, 0x160080
	global_load_lds_dwordx4 v[0:1], off
	v_lshl_add_u64 v[0:1], v[2:3], 0, s[12:13]
	s_mov_b32 m0, s44
	s_addc_u32 s15, s27, 0
	global_load_lds_dwordx4 v[0:1], off
	s_add_i32 m0, s34, 0x1c000
	v_lshl_add_u64 v[0:1], s[14:15], 0, v[128:129]
	global_load_lds_dwordx4 v[0:1], off
	v_lshl_add_u64 v[0:1], s[14:15], 0, v[130:131]
	s_add_i32 m0, s34, 0x1e000
	s_sext_i32_i8 s51, s5
	global_load_lds_dwordx4 v[0:1], off
	s_waitcnt vmcnt(8)
	s_barrier
	v_bfe_u32 v1, v226, 4, 2
	v_and_b32_e32 v0, 15, v226
	v_lshlrev_b32_e32 v2, 4, v1
	s_waitcnt vmcnt(0)
	v_lshl_or_b32 v152, s1, 6, v0
	v_lshl_or_b32 v0, v0, 6, v2
	v_lshlrev_b32_e32 v2, 2, v226
	v_and_b32_e32 v2, 32, v2
	v_bitop3_b32 v3, v0, s17, v2 bitop3:0xde
	v_bitop3_b32 v153, v0, s18, v2 bitop3:0xde
	v_lshl_or_b32 v154, v1, 2, s20
	v_lshrrev_b32_e32 v1, 1, v8
	v_mul_lo_u32 v0, v9, s0
	s_cmpk_lt_u32 s4, 0x100
	v_mad_u64_u32 v[0:1], s[4:5], v1, s16, v[0:1]
	v_or_b32_e32 v0, v0, v10
	s_mov_b64 s[18:19], 0x160080
	v_add_lshl_u32 v0, v0, v11, 1
	v_mov_b32_e32 v1, v129
	v_lshl_add_u64 v[132:133], v[0:1], 0, s[18:19]
	v_lshrrev_b32_e32 v1, 1, v12
	v_mul_lo_u32 v0, v13, s0
	v_mad_u64_u32 v[0:1], s[0:1], v1, s16, v[0:1]
	s_waitcnt vmcnt(6)
	v_or_b32_e32 v0, v0, v14
	s_cselect_b64 s[14:15], -1, 0
	v_add_lshl_u32 v0, v0, v15, 1
	v_mov_b32_e32 v1, v129
	s_add_i32 s46, 0, 0x10000
	s_add_i32 s47, 0, 0x14000
	s_ashr_i32 s45, s86, 31
	v_lshl_add_u64 v[134:135], v[0:1], 0, s[18:19]
	v_mov_b64_e32 v[136:137], 0x100
	v_mov_b64_e32 v[138:139], 0xff
	v_add_u32_e32 v155, s46, v153
	v_add_u32_e32 v156, s47, v153
	v_add_u32_e32 v157, 0, v3
	s_mov_b64 s[16:17], 0x100000
	s_mov_b64 s[18:19], 0x120000
	s_mov_b64 s[20:21], 0x140000
	s_barrier
	s_branch .LBB0_1087
